# v80_a3_logical_wave_roles_permuted_for_simd_balance
# baseline (speedup 1.0000x reference)
; #define LAS __attribute__((address_space(3)))
; __device__ __forceinline__ float bf2f(bf16_t v) { return __uint_as_float((unsigned)v << 16); }
; __device__ __forceinline__ unsigned f2bf(float f) { return (unsigned)__builtin_bit_cast(unsigned short, (__bf16)f); }
; #define X make_ctx(lds_raw)
;     bf16_t* proj = (bf16_t*)(a->ws + WS_BIG);
;     LAS bf16_t* qgs = (LAS bf16_t*)X.lds; LAS bf16_t* kgs = (LAS bf16_t*)(X.lds + 128 * GP * 2); LAS bf16_t* vT = (LAS bf16_t*)(X.lds + 256 * GP * 2); LAS float* segtot = (LAS float*)(X.lds + 512 * GP * 2);
;     const int fr = X.lane & 15, fq = X.lane >> 4, w = X.wave, i0 = 16 * w;
;     for (int unit = blockIdx.x; unit < 512; unit += gridDim.x) {
;         const int bh = unit >> 5, n = unit & 31, b = bh >> 2, h = bh & 3, t0 = b * SEQ + n * 128;
;         __syncthreads();
;         { float bc[32], tot; gla_bcum(a, X.tid, t0, h, segtot, (LAS float*)vT, bc, tot);
;           const int d = X.tid & 127, seg = X.tid >> 7;
; #pragma unroll
;           for (int r = 0; r < 32; ++r) { const int i = seg * 32 + r; const bf16_t* row = proj + (size_t)(t0 + i) * NMAIN + h * 128 + d;
;               const float qv = bf2f(row[C_GQ]), kv = bf2f(row[C_GK]);
;               qgs[i * GP + d] = (bf16_t)f2bf(qv * 0.08838834764831845f * __expf(bc[r])); kgs[i * GP + d] = (bf16_t)f2bf(kv * __expf(-bc[r])); } }
;         gla_stage_vT(proj, X.tid, t0, h, vT);
;         __syncthreads();
;         bf16x8 afr[4];
; #pragma unroll
;         for (int ks = 0; ks < 4; ++ks) afr[ks] = *(const LAS bf16x8*)(qgs + (i0 + fr) * GP + 32 * ks + 8 * fq);
;         f32x4 acc[16];
; #pragma unroll
;         for (int nt = 0; nt < 16; ++nt) acc[nt] = (f32x4){0.f, 0.f, 0.f, 0.f};
;         for (int jt = 0; jt <= (w | 1); ++jt) {
.LBB0_475:
	s_mov_b64 s[10:11], s[86:87]
	v_bfe_u32 v84, v186, 8, 1
	v_mul_u32_u24_e32 v84, 0xc0, v84
	v_xor_b32_e32 v84, v186, v84
	s_waitcnt vmcnt(0)
	s_barrier
	s_and_b64 vcc, exec, s[4:5]
	v_readfirstlane_b32 s1, v84
	s_cbranch_vccnz .LBB0_490
	s_load_dwordx4 s[12:15], s[10:11], 0x98
	s_load_dwordx4 s[16:19], s[10:11], 0x38
	s_ashr_i32 s2, s1, 6
	v_and_b32_e32 v86, 15, v84
	v_lshlrev_b32_e32 v2, 2, v84
	s_waitcnt lgkmcnt(0)
	s_add_u32 s22, s14, 0x4f00000
	s_addc_u32 s23, s15, 0
	s_lshl_b32 s3, s2, 4
	s_or_b32 s6, s2, 1
	s_cmp_gt_i32 s2, -1
	s_cselect_b64 s[38:39], -1, 0
	s_ashr_i32 s24, s1, 7
	v_or_b32_e32 v0, s3, v86
	s_movk_i32 s0, 0x110
	s_cmp_gt_i32 s24, -1
	v_ashrrev_i32_e32 v3, 31, v2
	v_mul_lo_u32 v0, v0, s0
	s_cselect_b64 s[40:41], -1, 0
	s_max_i32 s9, s6, 0
	v_lshl_add_u64 v[2:3], v[2:3], 2, s[14:15]
	s_mov_b64 s[6:7], 0x100000
	v_bfe_u32 v4, v84, 4, 2
	v_add_u32_e32 v5, 0, v0
	v_mov_b32_e32 v0, 0x5500
	v_and_b32_e32 v88, 0x7f, v84
	v_lshl_add_u64 v[90:91], v[2:3], 0, s[6:7]
	s_add_i32 s6, 0, 0x22000
	v_ashrrev_i32_e32 v119, 2, v84
	v_lshl_or_b32 v89, v4, 2, s3
	v_mad_u32_u24 v6, v86, s0, v0
	v_mov_b32_e32 v1, 0
	v_lshl_add_u32 v118, v88, 2, s6
	v_and_b32_e32 v120, 0xffffffe0, v119
	v_lshlrev_b32_e32 v0, 1, v88
	s_movk_i32 s6, 0x88
	v_or_b32_e32 v182, 31, v119
	v_lshl_add_u64 v[92:93], s[22:23], 0, v[0:1]
	v_mul_lo_u32 v0, v120, s6
	v_mad_u64_u32 v[2:3], s[6:7], v182, s6, v[88:89]
	s_add_i32 s1, 0, 0x11000
	v_lshlrev_b32_e32 v8, 4, v84
	v_lshl_add_u32 v183, v2, 1, 0
	v_lshrrev_b32_e32 v2, 4, v84
	v_add_u32_e32 v117, s1, v8
	v_ashrrev_i32_e32 v85, 31, v84
	v_mul_lo_u32 v2, v2, s0
	v_and_b32_e32 v8, 0xf0, v8
	v_lshlrev_b64 v[94:95], 4, v[84:85]
	v_add3_u32 v85, s1, v2, v8
	v_add_u32_e32 v2, 0x200, v84
	v_ashrrev_i32_e32 v3, 31, v2
	v_lshlrev_b64 v[96:97], 4, v[2:3]
	v_lshrrev_b32_e32 v2, 4, v2
	v_mul_lo_u32 v2, v2, s0
	v_add3_u32 v184, s1, v2, v8
	v_add_u32_e32 v2, 0x400, v84
	v_ashrrev_i32_e32 v3, 31, v2
	v_lshlrev_b64 v[98:99], 4, v[2:3]
	v_lshrrev_b32_e32 v2, 4, v2
	v_mul_lo_u32 v2, v2, s0
	v_add3_u32 v185, s1, v2, v8
	v_add_u32_e32 v2, 0x600, v84
	v_ashrrev_i32_e32 v3, 31, v2
	v_lshlrev_b64 v[100:101], 4, v[2:3]
	v_lshrrev_b32_e32 v2, 4, v2
	v_mul_lo_u32 v2, v2, s0
	v_add3_u32 v191, s1, v2, v8
	v_add_u32_e32 v2, 0x800, v84
	v_ashrrev_i32_e32 v3, 31, v2
	v_lshlrev_b64 v[102:103], 4, v[2:3]
	v_lshrrev_b32_e32 v2, 4, v2
	v_mul_lo_u32 v2, v2, s0
	v_add3_u32 v192, s1, v2, v8
	v_add_u32_e32 v2, 0xa00, v84
	v_ashrrev_i32_e32 v3, 31, v2
	v_lshlrev_b64 v[104:105], 4, v[2:3]
	v_lshrrev_b32_e32 v2, 4, v2
	v_mul_lo_u32 v2, v2, s0
	v_add3_u32 v193, s1, v2, v8
	v_add_u32_e32 v2, 0xc00, v84
	v_ashrrev_i32_e32 v3, 31, v2
	v_lshlrev_b64 v[106:107], 4, v[2:3]
	v_lshrrev_b32_e32 v2, 4, v2
	v_mul_lo_u32 v2, v2, s0
	v_add3_u32 v194, s1, v2, v8
	v_add_u32_e32 v2, 0xe00, v84
	v_ashrrev_i32_e32 v3, 31, v2
	v_or_b32_e32 v0, v0, v88
	v_lshlrev_b64 v[108:109], 4, v[2:3]
	v_lshrrev_b32_e32 v2, 4, v2
	v_and_b32_e32 v87, 48, v84
	s_mul_i32 s8, s2, 0x2200
	v_lshl_add_u32 v121, v0, 1, 0
	v_lshlrev_b32_e32 v0, 3, v84
	v_mul_lo_u32 v2, v2, s0
	v_add_u32_e32 v112, s1, v87
	v_mul_u32_u24_e32 v7, 0x880, v4
	v_and_b32_e32 v0, 24, v0
	v_lshl_add_u32 v9, v119, 1, s1
	v_add3_u32 v195, s1, v2, v8
	s_add_i32 s1, s8, 0
	v_lshlrev_b32_e32 v2, 1, v86
	v_bfe_u32 v3, v84, 2, 4
	v_add3_u32 v196, s1, v2, v7
	v_or_b32_e32 v197, s3, v3
	v_mul_u32_u24_e32 v3, 0x220, v3
	v_lshlrev_b32_e32 v7, 1, v0
	v_add3_u32 v198, s1, v3, v7
	s_mul_i32 s1, s2, 0x1100
	s_movk_i32 s14, 0x440
	v_mov_b32_e32 v3, s1
	v_mad_u32_u24 v3, v4, s14, v3
	v_mul_u32_u24_e32 v116, 0x110, v86
	v_or_b32_e32 v2, v3, v2
	v_add_u32_e32 v199, 0, v2
	v_add3_u32 v2, v116, v87, 0
	s_add_i32 s1, s1, 0
	v_mul_u32_u24_e32 v10, 0x110, v0
	v_add_u32_e32 v200, 0x8800, v2
	v_mov_b32_e32 v2, s1
	s_mov_b32 s37, 0
	v_or_b32_e32 v113, 1, v89
	v_or_b32_e32 v114, 2, v89
	v_or_b32_e32 v115, 3, v89
	v_or_b32_e32 v122, 1, v120
	v_add_u32_e32 v123, 0x110, v121
	v_or_b32_e32 v124, 2, v120
	v_add_u32_e32 v125, 0x220, v121
	v_or_b32_e32 v126, 3, v120
	v_add_u32_e32 v127, 0x330, v121
	v_or_b32_e32 v128, 4, v120
	v_add_u32_e32 v129, 0x440, v121
	v_or_b32_e32 v130, 5, v120
	v_add_u32_e32 v131, 0x550, v121
	v_or_b32_e32 v132, 6, v120
	v_add_u32_e32 v133, 0x660, v121
	v_or_b32_e32 v134, 7, v120
	v_add_u32_e32 v135, 0x770, v121
	v_or_b32_e32 v136, 8, v120
	v_add_u32_e32 v137, 0x880, v121
	v_or_b32_e32 v138, 9, v120
	v_add_u32_e32 v139, 0x990, v121
	v_or_b32_e32 v140, 10, v120
	v_add_u32_e32 v141, 0xaa0, v121
	v_or_b32_e32 v142, 11, v120
	v_add_u32_e32 v143, 0xbb0, v121
	v_or_b32_e32 v144, 12, v120
	v_add_u32_e32 v145, 0xcc0, v121
	v_or_b32_e32 v146, 13, v120
	v_add_u32_e32 v147, 0xdd0, v121
	v_or_b32_e32 v148, 14, v120
	v_add_u32_e32 v149, 0xee0, v121
	v_or_b32_e32 v150, 15, v120
	v_add_u32_e32 v151, 0xff0, v121
	v_or_b32_e32 v152, 16, v120
	v_add_u32_e32 v153, 0x1100, v121
	v_or_b32_e32 v154, 17, v120
	v_add_u32_e32 v155, 0x1210, v121
	v_or_b32_e32 v156, 18, v120
	v_add_u32_e32 v157, 0x1320, v121
	v_or_b32_e32 v158, 19, v120
	v_add_u32_e32 v159, 0x1430, v121
	v_or_b32_e32 v160, 20, v120
	v_add_u32_e32 v161, 0x1540, v121
	v_or_b32_e32 v162, 21, v120
	v_add_u32_e32 v163, 0x1650, v121
	v_or_b32_e32 v164, 22, v120
	v_add_u32_e32 v165, 0x1760, v121
	v_or_b32_e32 v166, 23, v120
	v_add_u32_e32 v167, 0x1870, v121
	v_or_b32_e32 v168, 24, v120
	v_add_u32_e32 v169, 0x1980, v121
	v_or_b32_e32 v170, 25, v120
	v_add_u32_e32 v171, 0x1a90, v121
	v_or_b32_e32 v172, 26, v120
	v_add_u32_e32 v173, 0x1ba0, v121
	v_or_b32_e32 v174, 27, v120
	v_add_u32_e32 v175, 0x1cb0, v121
	v_or_b32_e32 v176, 28, v120
	v_add_u32_e32 v177, 0x1dc0, v121
	v_or_b32_e32 v178, 29, v120
	v_add_u32_e32 v179, 0x1ed0, v121
	v_or_b32_e32 v180, 30, v120
	v_add_u32_e32 v181, 0x1fe0, v121
	s_add_i32 s3, s9, 1
	s_add_i32 s24, s24, 1
	v_mad_u32_u24 v201, v86, s0, 0
	v_mad_u32_u24 v202, v86, s0, v2
	s_movk_i32 s25, 0x1000
	s_movk_i32 s26, 0x2000
	s_movk_i32 s27, 0x3000
	s_movk_i32 s28, 0x4000
	s_movk_i32 s29, 0x5000
	s_movk_i32 s30, 0x6000
	s_movk_i32 s31, 0x7000
	s_mov_b32 s33, 0xbfb8aa3b
	s_mov_b32 s34, 0x800000
	s_mov_b32 s35, 0x3f317217
	s_mov_b32 s46, 0x7f800000
	s_mov_b32 s47, 0x3d800000
	s_movk_i32 s48, 0x2a00
	v_lshlrev_b32_e32 v110, 1, v0
	v_add_u32_e32 v203, v9, v10
	v_add_u32_e32 v204, v5, v87
	v_add_u32_e32 v205, v112, v6
	v_mov_b32_e32 v206, 0x358637bd
	s_mov_b32 s49, 0xf800000
	v_mov_b32_e32 v207, 0x260
	v_lshlrev_b32_e32 v208, 2, v86
	s_mov_b64 s[14:15], 0x1000
	v_mov_b32_e32 v209, 0x41b17218
	s_mov_b32 s42, s82
	s_branch .LBB0_478
